# baseline (speedup 1.0000x reference)
; template <int LSEL>
; __device__ __forceinline__ void hy_apply(const HyRaw& rw, float w0, float w1, float w2, float bias, bf16_t* dst, int toZ) {
;     ...
;     const int tok = (tid + 512 * it) * 8;
;     const int b = tok / L, s = tok - b * L;
;     const uint4 u = rw.u[it];
;     unsigned pw = (unsigned)__builtin_amdgcn_update_dpp(0, (int)u.w, 0x138, 0xf, 0xf, false);
;     unsigned nx = (unsigned)__builtin_amdgcn_update_dpp(0, (int)u.x, 0x130, 0xf, 0xf, false);
;     float x[10];
;     x[0] = hi2f(pw);
;     x[9] = lo2f(nx);
;     if (lane == 0) x[0] = bf2f(rw.edge[it]);
;     if (lane == 63) x[9] = bf2f(rw.edge[it]);
;     if (s == 0) x[0] = 0.f;
;     if (s + 8 >= L) x[9] = 0.f;
;     x[1] = lo2f(u.x); x[2] = hi2f(u.x); x[3] = lo2f(u.y); x[4] = hi2f(u.y);
;     x[5] = lo2f(u.z); x[6] = hi2f(u.z); x[7] = lo2f(u.w); x[8] = hi2f(u.w);
;     float o[8];
; #pragma unroll
;     for (int j = 0; j < 8; ++j) o[j] = w0 * x[j] + w1 * x[j + 1] + w2 * x[j + 2] + bias;
;     uint4 ou;
;     ou.x = pack2(o[0], o[1]); ou.y = pack2(o[2], o[3]); ou.z = pack2(o[4], o[5]); ou.w = pack2(o[6], o[7]);
;     *(uint4*)(dst + (toZ ? b * RS + PADF + s : b * HyC<LSEL>::XS + s)) = ou;
;   }
; template <int LSEL>
; __device__ __forceinline__ void hy_conv(const bf16_t* Z, const bf16_t* G, f32x4 (&acc)[4][4], int w, int lane) {
;   constexpr int L = HyC<LSEL>::L, NB = HyC<LSEL>::NB, BPT = HyC<LSEL>::BPT, RS = HyC<LSEL>::RS, PADF = HyC<LSEL>::PADF;
;   const int r = lane & 15, quad = lane >> 4;
;   const int zb = (LSEL ? (r & 7) * RS + (r >> 3) * 64 : r * RS) + PADF + quad * 8;
;   const int s = (8 - (r & 7)) & 7;
;   const bool t2 = (s & 4) != 0, t1 = (s & 2) != 0;
;   const unsigned sh = (s & 1) * 16;
;   const int q0 = w * 4;
;   const int i_lo = q0 * BPT, i_hi = (q0 + 4) * BPT - 1;
;   for (int d = i_lo - (NB - 1); d <= i_hi; ++d) {
;     bf16x8 bf[4][2];
; #pragma unroll
;     for (int k = 0; k < 4; ++k) {
;       int js = (q0 + k) * BPT - d;
;       js = min(max(js, LSEL ? -1 : 0), NB - 1);
;       const bf16_t* bp = Z + zb + 64 * js;
;       bf[k][0] = *(const bf16x8*)bp;
;       bf[k][1] = *(const bf16x8*)(bp + 32);
;     }
;     const bf16_t* gb = G + (L - 64 * d + 8 * quad - r - s);
;     bf16x8 F[6];
; #pragma unroll
;     for (int u = 0; u < 6; ++u) F[u] = hy_afrag(gb + 16 * (u - 3), t2, t1, sh);
.LBB0_833:
	s_or_b64 exec, exec, s[6:7]
	v_add_u32_e32 v41, 0x7000, v74
	v_ashrrev_i32_e32 v42, 31, v41
	v_lshrrev_b32_e32 v42, 21, v42
	v_add_u32_e32 v42, v41, v42
	v_and_b32_e32 v54, 0xfffff800, v42
	v_cmp_ne_u32_e64 s[4:5], v41, v54
	v_ashrrev_i32_e32 v53, 11, v42
	v_and_b32_e32 v44, 0xffff0000, v36
	v_cndmask_b32_e64 v42, 0, v0, s[4:5]
	v_lshlrev_b32_e32 v0, 16, v36
	v_lshlrev_b32_e32 v45, 16, v37
	v_pk_mov_b32 v[36:37], v[36:37], v[38:39] op_sel:[1,0]
	v_sub_u32_e32 v43, v41, v54
	v_and_b32_e32 v37, 16, v37
	v_and_b32_e32 v36, 0xffff0000, v36
	s_movk_i32 s4, 0x7f8
	v_and_b32_e32 v47, 16, v39
	v_and_b32_e32 v46, 0xffff0000, v38
	v_lshlrev_b32_e32 v49, 16, v39
	v_and_b32_e32 v51, 0xffff0000, v39
	v_lshlrev_b32_e32 v39, 16, v38
	v_mov_b32_e32 v38, v36
	v_pk_mov_b32 v[36:37], v[44:45], v[36:37] op_sel:[1,0]
	v_cmp_gt_i32_e64 s[4:5], s4, v43
	v_mov_b32_e32 v43, v44
	v_pk_mul_f32 v[36:37], v[72:73], v[36:37]
	v_pk_mul_f32 v[42:43], v[66:67], v[42:43]
	v_pk_fma_f32 v[36:37], v[64:65], v[44:45], v[36:37]
	v_pk_fma_f32 v[42:43], v[70:71], v[0:1], v[42:43] op_sel_hi:[1,0,1]
	v_pk_fma_f32 v[36:37], v[68:69], v[38:39], v[36:37]
	v_pk_fma_f32 v[42:43], v[68:69], v[44:45], v[42:43]
	v_pk_add_f32 v[44:45], v[2:3], v[36:37]
	v_pk_mov_b32 v[36:37], v[38:39], v[46:47] op_sel:[1,0]
	v_mov_b32_e32 v48, v46
	v_pk_mul_f32 v[36:37], v[72:73], v[36:37]
	v_mov_b32_e32 v50, v49
	v_pk_fma_f32 v[36:37], v[64:65], v[38:39], v[36:37]
	v_cndmask_b32_e64 v41, 0, v40, s[4:5]
	v_pk_fma_f32 v[36:37], v[68:69], v[48:49], v[36:37]
	v_mov_b32_e32 v40, v51
	v_pk_add_f32 v[38:39], v[2:3], v[36:37]
	v_pk_mul_f32 v[36:37], v[72:73], v[50:51]
	v_pk_add_f32 v[42:43], v[2:3], v[42:43]
	v_pk_fma_f32 v[36:37], v[64:65], v[48:49], v[36:37]
	v_cvt_pk_bf16_f32 v38, v38, v39
	v_pk_fma_f32 v[36:37], v[68:69], v[40:41], v[36:37]
	v_sub_u32_e32 v0, v74, v54
	v_pk_add_f32 v[2:3], v[2:3], v[36:37]
	v_and_b32_e32 v52, 63, v150
	v_cvt_pk_bf16_f32 v39, v2, v3
	v_mul_i32_i24_e32 v2, 0x1010, v53
	v_cvt_pk_bf16_f32 v36, v42, v43
	v_cvt_pk_bf16_f32 v37, v44, v45
	v_lshl_add_u32 v0, v0, 1, v2
	ds_write_b128 v0, v[36:39] offset:57344
	v_sub_u32_e32 v0, 0, v52
	v_and_b32_e32 v2, 4, v0
	v_cmp_eq_u32_e64 s[4:5], 0, v2
	v_and_b32_e32 v2, 2, v0
	v_lshlrev_b32_e32 v152, 4, v0
	v_and_b32_e32 v0, 7, v0
	v_and_b32_e32 v165, 15, v150
	v_ashrrev_i32_e32 v164, 6, v150
	v_cmp_eq_u32_e64 s[6:7], 0, v2
	v_and_b32_e32 v2, 48, v150
	s_movk_i32 s10, 0x1010
	v_add_lshl_u32 v0, v0, v165, 1
	v_mad_u32_u24 v153, v165, s10, v2
	v_sub_u32_e32 v0, v2, v0
	v_lshlrev_b32_e32 v2, 9, v164
	v_sub_u32_e32 v155, v0, v2
	v_mov_b32_e32 v2, v1
	v_mov_b32_e32 v3, v1
	v_mov_b32_e32 v0, v1
	v_mov_b64_e32 v[38:39], v[2:3]
	v_mov_b64_e32 v[42:43], v[2:3]
	v_mov_b64_e32 v[46:47], v[2:3]
	v_mov_b64_e32 v[50:51], v[2:3]
	v_mov_b64_e32 v[54:55], v[2:3]
	v_mov_b64_e32 v[58:59], v[2:3]
	v_mov_b64_e32 v[62:63], v[2:3]
	v_mov_b64_e32 v[66:67], v[2:3]
	v_mov_b64_e32 v[70:71], v[2:3]
	v_mov_b64_e32 v[74:75], v[2:3]
	v_mov_b64_e32 v[78:79], v[2:3]
	v_mov_b64_e32 v[82:83], v[2:3]
	v_mov_b64_e32 v[86:87], v[2:3]
	v_mov_b64_e32 v[90:91], v[2:3]
	v_mov_b64_e32 v[94:95], v[2:3]
	v_mov_b64_e32 v[98:99], v[2:3]
	s_mov_b32 s8, 31
	s_mov_b32 s9, 0
	v_add_u32_e32 v154, 0xf80, v153
	v_mov_b64_e32 v[36:37], v[0:1]
	v_mov_b64_e32 v[40:41], v[0:1]
	v_mov_b64_e32 v[44:45], v[0:1]
	v_mov_b64_e32 v[48:49], v[0:1]
	v_mov_b64_e32 v[52:53], v[0:1]
	v_mov_b64_e32 v[56:57], v[0:1]
	v_mov_b64_e32 v[60:61], v[0:1]
	v_mov_b64_e32 v[64:65], v[0:1]
	v_mov_b64_e32 v[68:69], v[0:1]
	v_mov_b64_e32 v[72:73], v[0:1]
	v_mov_b64_e32 v[76:77], v[0:1]
	v_mov_b64_e32 v[80:81], v[0:1]
	v_mov_b64_e32 v[84:85], v[0:1]
	v_mov_b64_e32 v[88:89], v[0:1]
	v_mov_b64_e32 v[92:93], v[0:1]
	v_mov_b64_e32 v[96:97], v[0:1]
	v_lshrrev_b32_e32 v176, 3, v152
	v_and_b32_e32 v176, 12, v176
	v_add_u32_e32 v176, v176, v155
	v_add_u32_e32 v176, 0x228a0, v176
	s_waitcnt lgkmcnt(0)
	s_barrier
	ds_read2_b32 v[180:181], v176 offset0:32 offset1:33
	ds_read2_b32 v[182:183], v176 offset0:34 offset1:35
	ds_read_b32 v184, v176 offset:144
	ds_read2_b32 v[186:187], v176 offset0:40 offset1:41
	ds_read2_b32 v[188:189], v176 offset0:42 offset1:43
	ds_read_b32 v190, v176 offset:176
	s_waitcnt lgkmcnt(0)
	v_alignbit_b32 v108, v181, v180, v152
	v_alignbit_b32 v109, v182, v181, v152
	v_alignbit_b32 v110, v183, v182, v152
	v_alignbit_b32 v111, v184, v183, v152
	v_alignbit_b32 v120, v187, v186, v152
	v_alignbit_b32 v121, v188, v187, v152
	v_alignbit_b32 v122, v189, v188, v152
	v_alignbit_b32 v123, v190, v189, v152
	ds_read2_b32 v[180:181], v176 offset1:1
	ds_read2_b32 v[182:183], v176 offset0:2 offset1:3
	ds_read_b32 v184, v176 offset:16
	ds_read2_b32 v[186:187], v176 offset0:8 offset1:9
	ds_read2_b32 v[188:189], v176 offset0:10 offset1:11
	ds_read_b32 v190, v176 offset:48
	ds_read2_b32 v[192:193], v176 offset0:16 offset1:17
	ds_read2_b32 v[194:195], v176 offset0:18 offset1:19
	ds_read_b32 v196, v176 offset:80
	ds_read2_b32 v[198:199], v176 offset0:24 offset1:25
	ds_read2_b32 v[200:201], v176 offset0:26 offset1:27
	ds_read_b32 v202, v176 offset:112
	s_branch .LBB0_835

; template <int LSEL>
; __device__ __forceinline__ void hy_conv(const bf16_t* Z, const bf16_t* G, f32x4 (&acc)[4][4], int w, int lane) {
;     ...
;   for (int d = i_lo - (NB - 1); d <= i_hi; ++d) {
;     bf16x8 bf[4][2];
; #pragma unroll
;     for (int k = 0; k < 4; ++k) {
;       int js = (q0 + k) * BPT - d;
;       js = min(max(js, LSEL ? -1 : 0), NB - 1);
;       const bf16_t* bp = Z + zb + 64 * js;
;       bf[k][0] = *(const bf16x8*)bp;
;       bf[k][1] = *(const bf16x8*)(bp + 32);
;     }
;     const bf16_t* gb = G + (L - 64 * d + 8 * quad - r - s);
;     bf16x8 F[6];
; #pragma unroll
;     for (int u = 0; u < 6; ++u) F[u] = hy_afrag(gb + 16 * (u - 3), t2, t1, sh);
; #pragma unroll
;     for (int k = 0; k < 4; ++k) {
;       const int js = (q0 + k) * BPT - d;
;       const bool valid = LSEL ? (js >= -1 && js <= NB - 1) : (js >= 0 && js <= NB - 1);
;       if (valid) {
; #pragma unroll
;         for (int mt = 0; mt < 4; ++mt) {
;           acc[k][mt] = __builtin_amdgcn_mfma_f32_16x16x32_bf16(F[3 - mt], bf[k][0], acc[k][mt], 0, 0, 0);
;           acc[k][mt] = __builtin_amdgcn_mfma_f32_16x16x32_bf16(F[5 - mt], bf[k][1], acc[k][mt], 0, 0, 0);
;         }
;       }
.LBB0_835:
	s_waitcnt lgkmcnt(0)
	v_mov_b32_e32 v140, v108
	v_mov_b32_e32 v141, v109
	v_mov_b32_e32 v142, v110
	v_mov_b32_e32 v143, v111
	v_mov_b32_e32 v144, v120
	v_mov_b32_e32 v145, v121
	v_mov_b32_e32 v146, v122
	v_mov_b32_e32 v147, v123
	v_alignbit_b32 v108, v181, v180, v152
	v_alignbit_b32 v109, v182, v181, v152
	v_alignbit_b32 v110, v183, v182, v152
	v_alignbit_b32 v111, v184, v183, v152
	v_alignbit_b32 v120, v187, v186, v152
	v_alignbit_b32 v121, v188, v187, v152
	v_alignbit_b32 v122, v189, v188, v152
	v_alignbit_b32 v123, v190, v189, v152
	v_alignbit_b32 v124, v193, v192, v152
	v_alignbit_b32 v125, v194, v193, v152
	v_alignbit_b32 v126, v195, v194, v152
	v_alignbit_b32 v127, v196, v195, v152
	v_alignbit_b32 v136, v199, v198, v152
	v_alignbit_b32 v137, v200, v199, v152
	v_alignbit_b32 v138, v201, v200, v152
	v_alignbit_b32 v139, v202, v201, v152
	s_add_i32 s12, s8, 1
	v_med3_i32 v0, s12, 0, 31
	v_lshl_add_u32 v0, v0, 7, v153
	s_add_i32 s11, s8, 2
	ds_read_b128 v[128:131], v0
	ds_read_b128 v[132:135], v0 offset:64
	v_med3_i32 v0, s11, 0, 31
	s_add_i32 s10, s8, 3
	v_lshl_add_u32 v0, v0, 7, v153
	s_min_u32 s13, s10, 31
	ds_read_b128 v[112:115], v0
	ds_read_b128 v[116:119], v0 offset:64
	v_lshl_add_u32 v0, s13, 7, v153
	ds_read_b128 v[100:103], v0
	ds_read_b128 v[104:107], v0 offset:64
	v_add_u32_e32 v0, s9, v154
	ds_read_b128 v[166:169], v0
	ds_read_b128 v[170:173], v0 offset:64
	v_add_u32_e32 v0, s9, v176
	v_add_u32_e32 v0, 0xffffff80, v0
	ds_read2_b32 v[180:181], v0 offset1:1
	ds_read2_b32 v[182:183], v0 offset0:2 offset1:3
	ds_read_b32 v184, v0 offset:16
	ds_read2_b32 v[186:187], v0 offset0:8 offset1:9
	ds_read2_b32 v[188:189], v0 offset0:10 offset1:11
	ds_read_b32 v190, v0 offset:48
	s_waitcnt lgkmcnt(6)
	ds_read2_b32 v[192:193], v0 offset0:16 offset1:17
	ds_read2_b32 v[194:195], v0 offset0:18 offset1:19
	ds_read_b32 v196, v0 offset:80
	ds_read2_b32 v[198:199], v0 offset0:24 offset1:25
	ds_read2_b32 v[200:201], v0 offset0:26 offset1:27
	ds_read_b32 v202, v0 offset:112
	s_cmp_gt_u32 s8, 31
	s_cbranch_scc1 .LBB0_839
	v_mfma_f32_16x16x32_bf16 v[96:99], v[136:139], v[166:169], v[96:99]
	v_mfma_f32_16x16x32_bf16 v[92:95], v[124:127], v[166:169], v[92:95]
	v_mfma_f32_16x16x32_bf16 v[88:91], v[120:123], v[166:169], v[88:91]
	v_mfma_f32_16x16x32_bf16 v[84:87], v[108:111], v[166:169], v[84:87]
	v_mfma_f32_16x16x32_bf16 v[96:99], v[144:147], v[170:173], v[96:99]
	v_mfma_f32_16x16x32_bf16 v[92:95], v[140:143], v[170:173], v[92:95]
	v_mfma_f32_16x16x32_bf16 v[88:91], v[136:139], v[170:173], v[88:91]
	v_mfma_f32_16x16x32_bf16 v[84:87], v[124:127], v[170:173], v[84:87]
	s_cmp_gt_u32 s12, 31
	s_cbranch_scc0 .LBB0_840

; template <int LSEL>
; __device__ __forceinline__ void hy_conv(const bf16_t* Z, const bf16_t* G, f32x4 (&acc)[4][4], int w, int lane) {
;   constexpr int L = HyC<LSEL>::L, NB = HyC<LSEL>::NB, BPT = HyC<LSEL>::BPT, RS = HyC<LSEL>::RS, PADF = HyC<LSEL>::PADF;
;   const int r = lane & 15, quad = lane >> 4;
;   const int zb = (LSEL ? (r & 7) * RS + (r >> 3) * 64 : r * RS) + PADF + quad * 8;
;   const int s = (8 - (r & 7)) & 7;
;   const bool t2 = (s & 4) != 0, t1 = (s & 2) != 0;
;   const unsigned sh = (s & 1) * 16;
;   const int q0 = w * 4;
;   const int i_lo = q0 * BPT, i_hi = (q0 + 4) * BPT - 1;
;   for (int d = i_lo - (NB - 1); d <= i_hi; ++d) {
;     bf16x8 bf[4][2];
; #pragma unroll
;     for (int k = 0; k < 4; ++k) {
;       int js = (q0 + k) * BPT - d;
;       js = min(max(js, LSEL ? -1 : 0), NB - 1);
;       const bf16_t* bp = Z + zb + 64 * js;
;       bf[k][0] = *(const bf16x8*)bp;
;       bf[k][1] = *(const bf16x8*)(bp + 32);
;     }
;     const bf16_t* gb = G + (L - 64 * d + 8 * quad - r - s);
;     bf16x8 F[6];
; #pragma unroll
;     for (int u = 0; u < 6; ++u) F[u] = hy_afrag(gb + 16 * (u - 3), t2, t1, sh);
.LBB0_926:
	s_or_b64 exec, exec, s[8:9]
	v_mov_b32_e32 v2, v1
	v_mov_b32_e32 v3, v1
	v_mov_b32_e32 v0, v1
	v_mov_b64_e32 v[6:7], v[2:3]
	v_mov_b64_e32 v[10:11], v[2:3]
	v_mov_b64_e32 v[14:15], v[2:3]
	v_mov_b64_e32 v[22:23], v[2:3]
	v_mov_b64_e32 v[26:27], v[2:3]
	v_mov_b64_e32 v[30:31], v[2:3]
	v_mov_b64_e32 v[34:35], v[2:3]
	v_mov_b64_e32 v[38:39], v[2:3]
	v_mov_b64_e32 v[42:43], v[2:3]
	v_mov_b64_e32 v[50:51], v[2:3]
	v_mov_b64_e32 v[54:55], v[2:3]
	v_mov_b64_e32 v[58:59], v[2:3]
	v_mov_b64_e32 v[62:63], v[2:3]
	v_mov_b64_e32 v[66:67], v[2:3]
	v_mov_b64_e32 v[70:71], v[2:3]
	v_mov_b64_e32 v[78:79], v[2:3]
	s_mov_b32 s8, 0
	s_mov_b32 s9, 31
	v_mov_b64_e32 v[4:5], v[0:1]
	v_mov_b64_e32 v[8:9], v[0:1]
	v_mov_b64_e32 v[12:13], v[0:1]
	v_mov_b64_e32 v[20:21], v[0:1]
	v_mov_b64_e32 v[24:25], v[0:1]
	v_mov_b64_e32 v[28:29], v[0:1]
	v_mov_b64_e32 v[32:33], v[0:1]
	v_mov_b64_e32 v[36:37], v[0:1]
	v_mov_b64_e32 v[40:41], v[0:1]
	v_mov_b64_e32 v[48:49], v[0:1]
	v_mov_b64_e32 v[52:53], v[0:1]
	v_mov_b64_e32 v[56:57], v[0:1]
	v_mov_b64_e32 v[60:61], v[0:1]
	v_mov_b64_e32 v[64:65], v[0:1]
	v_mov_b64_e32 v[68:69], v[0:1]
	v_mov_b64_e32 v[76:77], v[0:1]
	s_waitcnt lgkmcnt(0)
	s_barrier
	ds_read2_b32 v[180:181], v176 offset0:32 offset1:33
	ds_read2_b32 v[182:183], v176 offset0:34 offset1:35
	ds_read_b32 v184, v176 offset:144
	ds_read2_b32 v[186:187], v176 offset0:40 offset1:41
	ds_read2_b32 v[188:189], v176 offset0:42 offset1:43
	ds_read_b32 v190, v176 offset:176
	s_waitcnt lgkmcnt(0)
	v_alignbit_b32 v108, v181, v180, v152
	v_alignbit_b32 v109, v182, v181, v152
	v_alignbit_b32 v110, v183, v182, v152
	v_alignbit_b32 v111, v184, v183, v152
	v_alignbit_b32 v120, v187, v186, v152
	v_alignbit_b32 v121, v188, v187, v152
	v_alignbit_b32 v122, v189, v188, v152
	v_alignbit_b32 v123, v190, v189, v152
	ds_read2_b32 v[180:181], v176 offset1:1
	ds_read2_b32 v[182:183], v176 offset0:2 offset1:3
	ds_read_b32 v184, v176 offset:16
	ds_read2_b32 v[186:187], v176 offset0:8 offset1:9
	ds_read2_b32 v[188:189], v176 offset0:10 offset1:11
	ds_read_b32 v190, v176 offset:48
	ds_read2_b32 v[192:193], v176 offset0:16 offset1:17
	ds_read2_b32 v[194:195], v176 offset0:18 offset1:19
	ds_read_b32 v196, v176 offset:80
	ds_read2_b32 v[198:199], v176 offset0:24 offset1:25
	ds_read2_b32 v[200:201], v176 offset0:26 offset1:27
	ds_read_b32 v202, v176 offset:112
	s_branch .LBB0_928

; template <int LSEL>
; __device__ __forceinline__ void hy_conv(const bf16_t* Z, const bf16_t* G, f32x4 (&acc)[4][4], int w, int lane) {
;     ...
;   for (int d = i_lo - (NB - 1); d <= i_hi; ++d) {
;     bf16x8 bf[4][2];
; #pragma unroll
;     for (int k = 0; k < 4; ++k) {
;       int js = (q0 + k) * BPT - d;
;       js = min(max(js, LSEL ? -1 : 0), NB - 1);
;       const bf16_t* bp = Z + zb + 64 * js;
;       bf[k][0] = *(const bf16x8*)bp;
;       bf[k][1] = *(const bf16x8*)(bp + 32);
;     }
;     const bf16_t* gb = G + (L - 64 * d + 8 * quad - r - s);
;     bf16x8 F[6];
; #pragma unroll
;     for (int u = 0; u < 6; ++u) F[u] = hy_afrag(gb + 16 * (u - 3), t2, t1, sh);
; #pragma unroll
;     for (int k = 0; k < 4; ++k) {
;       const int js = (q0 + k) * BPT - d;
;       const bool valid = LSEL ? (js >= -1 && js <= NB - 1) : (js >= 0 && js <= NB - 1);
;       if (valid) {
; #pragma unroll
;         for (int mt = 0; mt < 4; ++mt) {
;           acc[k][mt] = __builtin_amdgcn_mfma_f32_16x16x32_bf16(F[3 - mt], bf[k][0], acc[k][mt], 0, 0, 0);
;           acc[k][mt] = __builtin_amdgcn_mfma_f32_16x16x32_bf16(F[5 - mt], bf[k][1], acc[k][mt], 0, 0, 0);
;         }
;       }
.LBB0_928:
	s_waitcnt lgkmcnt(0)
	v_mov_b32_e32 v140, v108
	v_mov_b32_e32 v141, v109
	v_mov_b32_e32 v142, v110
	v_mov_b32_e32 v143, v111
	v_mov_b32_e32 v144, v120
	v_mov_b32_e32 v145, v121
	v_mov_b32_e32 v146, v122
	v_mov_b32_e32 v147, v123
	v_alignbit_b32 v108, v181, v180, v152
	v_alignbit_b32 v109, v182, v181, v152
	v_alignbit_b32 v110, v183, v182, v152
	v_alignbit_b32 v111, v184, v183, v152
	v_alignbit_b32 v120, v187, v186, v152
	v_alignbit_b32 v121, v188, v187, v152
	v_alignbit_b32 v122, v189, v188, v152
	v_alignbit_b32 v123, v190, v189, v152
	v_alignbit_b32 v124, v193, v192, v152
	v_alignbit_b32 v125, v194, v193, v152
	v_alignbit_b32 v126, v195, v194, v152
	v_alignbit_b32 v127, v196, v195, v152
	v_alignbit_b32 v136, v199, v198, v152
	v_alignbit_b32 v137, v200, v199, v152
	v_alignbit_b32 v138, v201, v200, v152
	v_alignbit_b32 v139, v202, v201, v152
	s_add_i32 s12, s9, 1
	v_med3_i32 v0, s12, 0, 31
	v_lshl_add_u32 v0, v0, 7, v153
	s_add_i32 s11, s9, 2
	ds_read_b128 v[128:131], v0
	ds_read_b128 v[132:135], v0 offset:64
	v_med3_i32 v0, s11, 0, 31
	s_add_i32 s10, s9, 3
	v_lshl_add_u32 v0, v0, 7, v153
	s_min_u32 s13, s10, 31
	ds_read_b128 v[112:115], v0
	ds_read_b128 v[116:119], v0 offset:64
	v_lshl_add_u32 v0, s13, 7, v153
	ds_read_b128 v[100:103], v0
	ds_read_b128 v[104:107], v0 offset:64
	v_add_u32_e32 v0, s8, v154
	ds_read_b128 v[166:169], v0
	ds_read_b128 v[170:173], v0 offset:64
	v_add_u32_e32 v0, s8, v176
	v_add_u32_e32 v0, 0xffffff80, v0
	ds_read2_b32 v[180:181], v0 offset1:1
	ds_read2_b32 v[182:183], v0 offset0:2 offset1:3
	ds_read_b32 v184, v0 offset:16
	ds_read2_b32 v[186:187], v0 offset0:8 offset1:9
	ds_read2_b32 v[188:189], v0 offset0:10 offset1:11
	ds_read_b32 v190, v0 offset:48
	s_waitcnt lgkmcnt(6)
	ds_read2_b32 v[192:193], v0 offset0:16 offset1:17
	ds_read2_b32 v[194:195], v0 offset0:18 offset1:19
	ds_read_b32 v196, v0 offset:80
	ds_read2_b32 v[198:199], v0 offset0:24 offset1:25
	ds_read2_b32 v[200:201], v0 offset0:26 offset1:27
	ds_read_b32 v202, v0 offset:112
	s_cmp_gt_u32 s9, 31
	s_cbranch_scc1 .LBB0_932
	v_mfma_f32_16x16x32_bf16 v[76:79], v[136:139], v[166:169], v[76:79]
	v_mfma_f32_16x16x32_bf16 v[68:71], v[124:127], v[166:169], v[68:71]
	v_mfma_f32_16x16x32_bf16 v[64:67], v[120:123], v[166:169], v[64:67]
	v_mfma_f32_16x16x32_bf16 v[60:63], v[108:111], v[166:169], v[60:63]
	v_mfma_f32_16x16x32_bf16 v[76:79], v[144:147], v[170:173], v[76:79]
	v_mfma_f32_16x16x32_bf16 v[68:71], v[140:143], v[170:173], v[68:71]
	v_mfma_f32_16x16x32_bf16 v[64:67], v[136:139], v[170:173], v[64:67]
	v_mfma_f32_16x16x32_bf16 v[60:63], v[124:127], v[170:173], v[60:63]
	s_cmp_gt_u32 s12, 31
	s_cbranch_scc0 .LBB0_933

; template <int LSEL>
; __device__ __forceinline__ void hy_apply(const HyRaw& rw, float w0, float w1, float w2, float bias, bf16_t* dst, int toZ) {
;     ...
;     const int tok = (tid + 512 * it) * 8;
;     const int b = tok / L, s = tok - b * L;
;     const uint4 u = rw.u[it];
;     unsigned pw = (unsigned)__builtin_amdgcn_update_dpp(0, (int)u.w, 0x138, 0xf, 0xf, false);
;     unsigned nx = (unsigned)__builtin_amdgcn_update_dpp(0, (int)u.x, 0x130, 0xf, 0xf, false);
;     float x[10];
;     x[0] = hi2f(pw);
;     x[9] = lo2f(nx);
;     if (lane == 0) x[0] = bf2f(rw.edge[it]);
;     if (lane == 63) x[9] = bf2f(rw.edge[it]);
;     if (s == 0) x[0] = 0.f;
;     if (s + 8 >= L) x[9] = 0.f;
;     x[1] = lo2f(u.x); x[2] = hi2f(u.x); x[3] = lo2f(u.y); x[4] = hi2f(u.y);
;     x[5] = lo2f(u.z); x[6] = hi2f(u.z); x[7] = lo2f(u.w); x[8] = hi2f(u.w);
;     float o[8];
; #pragma unroll
;     for (int j = 0; j < 8; ++j) o[j] = w0 * x[j] + w1 * x[j + 1] + w2 * x[j + 2] + bias;
;     uint4 ou;
;     ou.x = pack2(o[0], o[1]); ou.y = pack2(o[2], o[3]); ou.z = pack2(o[4], o[5]); ou.w = pack2(o[6], o[7]);
;     *(uint4*)(dst + (toZ ? b * RS + PADF + s : b * HyC<LSEL>::XS + s)) = ou;
;   }
; template <int LSEL>
; __device__ __forceinline__ void hy_conv(const bf16_t* Z, const bf16_t* G, f32x4 (&acc)[4][4], int w, int lane) {
;   constexpr int L = HyC<LSEL>::L, NB = HyC<LSEL>::NB, BPT = HyC<LSEL>::BPT, RS = HyC<LSEL>::RS, PADF = HyC<LSEL>::PADF;
;   const int r = lane & 15, quad = lane >> 4;
;   const int zb = (LSEL ? (r & 7) * RS + (r >> 3) * 64 : r * RS) + PADF + quad * 8;
;   const int s = (8 - (r & 7)) & 7;
;   const bool t2 = (s & 4) != 0, t1 = (s & 2) != 0;
;   const unsigned sh = (s & 1) * 16;
;   const int q0 = w * 4;
;   const int i_lo = q0 * BPT, i_hi = (q0 + 4) * BPT - 1;
;   for (int d = i_lo - (NB - 1); d <= i_hi; ++d) {
;     bf16x8 bf[4][2];
; #pragma unroll
;     for (int k = 0; k < 4; ++k) {
;       int js = (q0 + k) * BPT - d;
;       js = min(max(js, LSEL ? -1 : 0), NB - 1);
;       const bf16_t* bp = Z + zb + 64 * js;
;       bf[k][0] = *(const bf16x8*)bp;
;       bf[k][1] = *(const bf16x8*)(bp + 32);
;     }
;     const bf16_t* gb = G + (L - 64 * d + 8 * quad - r - s);
;     bf16x8 F[6];
; #pragma unroll
;     for (int u = 0; u < 6; ++u) F[u] = hy_afrag(gb + 16 * (u - 3), t2, t1, sh);
.LBB0_1110:
	s_or_b64 exec, exec, s[6:7]
	v_add_u32_e32 v35, 0x7000, v74
	v_ashrrev_i32_e32 v36, 31, v35
	v_lshrrev_b32_e32 v36, 20, v36
	v_add_u32_e32 v37, v35, v36
	v_and_b32_e32 v48, 0xfffff000, v37
	v_and_b32_e32 v36, 0xffff0000, v3
	v_and_b32_e32 v39, 16, v3
	v_lshlrev_b32_e32 v3, 16, v3
	v_cmp_ne_u32_e64 s[4:5], v35, v48
	v_ashrrev_i32_e32 v46, 12, v37
	v_and_b32_e32 v38, 0xffff0000, v2
	v_sub_u32_e32 v37, v35, v48
	v_cndmask_b32_e64 v40, 0, v0, s[4:5]
	s_movk_i32 s4, 0xff8
	v_mov_b32_e32 v44, v3
	v_mov_b32_e32 v45, v36
	v_mov_b32_e32 v2, v38
	v_cmp_gt_i32_e64 s[4:5], s4, v37
	v_pk_mul_f32 v[44:45], v[72:73], v[44:45]
	v_and_b32_e32 v35, 16, v64
	v_cndmask_b32_e64 v37, 0, v34, s[4:5]
	v_and_b32_e32 v34, 0xffff0000, v63
	v_pk_fma_f32 v[44:45], v[60:61], v[2:3], v[44:45]
	v_lshlrev_b32_e32 v43, 16, v64
	v_mov_b32_e32 v42, v34
	v_pk_fma_f32 v[36:37], v[68:69], v[36:37], v[44:45]
	v_and_b32_e32 v44, 0xffff0000, v62
	v_lshlrev_b32_e32 v45, 16, v63
	v_pk_mov_b32 v[38:39], v[42:43], v[38:39] op_sel:[1,0]
	v_mov_b32_e32 v41, v44
	v_pk_mov_b32 v[34:35], v[44:45], v[34:35] op_sel:[1,0]
	v_lshlrev_b32_e32 v0, 16, v62
	v_pk_mul_f32 v[40:41], v[58:59], v[40:41]
	v_pk_mul_f32 v[34:35], v[72:73], v[34:35]
	v_pk_mul_f32 v[38:39], v[72:73], v[38:39]
	v_pk_fma_f32 v[40:41], v[70:71], v[0:1], v[40:41] op_sel_hi:[1,0,1]
	v_pk_fma_f32 v[34:35], v[60:61], v[44:45], v[34:35]
	v_pk_fma_f32 v[38:39], v[60:61], v[42:43], v[38:39]
	v_pk_fma_f32 v[40:41], v[68:69], v[44:45], v[40:41]
	v_pk_fma_f32 v[34:35], v[68:69], v[42:43], v[34:35]
	v_pk_fma_f32 v[2:3], v[68:69], v[2:3], v[38:39]
	v_sub_u32_e32 v0, v74, v48
	v_pk_add_f32 v[36:37], v[66:67], v[36:37]
	v_pk_add_f32 v[40:41], v[66:67], v[40:41]
	v_pk_add_f32 v[34:35], v[66:67], v[34:35]
	v_pk_add_f32 v[2:3], v[66:67], v[2:3]
	v_lshlrev_b32_e32 v0, 1, v0
	v_and_b32_e32 v47, 63, v4
	v_cvt_pk_bf16_f32 v37, v36, v37
	v_cvt_pk_bf16_f32 v36, v2, v3
	v_cvt_pk_bf16_f32 v35, v34, v35
	v_cvt_pk_bf16_f32 v34, v40, v41
	v_mad_i32_i24 v0, v46, s39, v0
	ds_write_b128 v0, v[34:37] offset:57472
	v_sub_u32_e32 v0, 0, v47
	v_and_b32_e32 v2, 4, v0
	v_cmp_eq_u32_e64 s[4:5], 0, v2
	v_and_b32_e32 v2, 2, v0
	v_and_b32_e32 v167, 64, v150
	v_and_b32_e32 v166, 7, v4
	v_cmp_eq_u32_e64 s[6:7], 0, v2
	v_lshlrev_b32_e32 v2, 1, v167
	v_mul_u32_u24_e32 v34, 0x2110, v166
	v_and_b32_e32 v35, 48, v4
	v_add3_u32 v154, v2, v34, v35
	v_lshlrev_b32_e32 v2, 4, v4
	v_lshlrev_b32_e32 v151, 4, v0
	v_and_b32_e32 v0, 7, v0
	v_and_b32_e32 v3, 15, v4
	v_and_b32_e32 v2, 0x80, v2
	v_ashrrev_i32_e32 v165, 6, v4
	v_mad_u32_u24 v2, v166, s39, v2
	s_movk_i32 s10, 0x2000
	v_add_lshl_u32 v0, v0, v3, 1
	v_add3_u32 v155, v2, v35, s10
	v_sub_u32_e32 v0, v35, v0
	v_lshlrev_b32_e32 v2, 10, v165
	v_sub_u32_e32 v156, v0, v2
	v_mov_b32_e32 v2, v1
	v_mov_b32_e32 v3, v1
	v_mov_b32_e32 v0, v1
	v_mov_b64_e32 v[36:37], v[2:3]
	v_mov_b64_e32 v[40:41], v[2:3]
	v_mov_b64_e32 v[44:45], v[2:3]
	v_mov_b64_e32 v[48:49], v[2:3]
	v_mov_b64_e32 v[52:53], v[2:3]
	v_mov_b64_e32 v[56:57], v[2:3]
	v_mov_b64_e32 v[60:61], v[2:3]
	v_mov_b64_e32 v[64:65], v[2:3]
	v_mov_b64_e32 v[68:69], v[2:3]
	v_mov_b64_e32 v[72:73], v[2:3]
	v_mov_b64_e32 v[76:77], v[2:3]
	v_mov_b64_e32 v[80:81], v[2:3]
	v_mov_b64_e32 v[84:85], v[2:3]
	v_mov_b64_e32 v[88:89], v[2:3]
	v_mov_b64_e32 v[92:93], v[2:3]
	v_mov_b64_e32 v[96:97], v[2:3]
	s_mov_b32 s8, 0
	s_mov_b32 s9, 64
	v_mov_b64_e32 v[34:35], v[0:1]
	v_mov_b64_e32 v[38:39], v[0:1]
	v_mov_b64_e32 v[42:43], v[0:1]
	v_mov_b64_e32 v[46:47], v[0:1]
	v_mov_b64_e32 v[50:51], v[0:1]
	v_mov_b64_e32 v[54:55], v[0:1]
	v_mov_b64_e32 v[58:59], v[0:1]
	v_mov_b64_e32 v[62:63], v[0:1]
	v_mov_b64_e32 v[66:67], v[0:1]
	v_mov_b64_e32 v[70:71], v[0:1]
	v_mov_b64_e32 v[74:75], v[0:1]
	v_mov_b64_e32 v[78:79], v[0:1]
	v_mov_b64_e32 v[82:83], v[0:1]
	v_mov_b64_e32 v[86:87], v[0:1]
	v_mov_b64_e32 v[90:91], v[0:1]
	v_mov_b64_e32 v[94:95], v[0:1]
	v_lshrrev_b32_e32 v176, 3, v151
	v_and_b32_e32 v176, 12, v176
	v_add_u32_e32 v176, v176, v156
	v_add_u32_e32 v176, 0x248a0, v176
	s_waitcnt lgkmcnt(0)
	s_barrier
	ds_read2_b32 v[180:181], v176 offset0:32 offset1:33
	ds_read2_b32 v[182:183], v176 offset0:34 offset1:35
	ds_read_b32 v184, v176 offset:144
	ds_read2_b32 v[186:187], v176 offset0:40 offset1:41
	ds_read2_b32 v[188:189], v176 offset0:42 offset1:43
	ds_read_b32 v190, v176 offset:176
	s_waitcnt lgkmcnt(0)
	v_alignbit_b32 v106, v181, v180, v151
	v_alignbit_b32 v107, v182, v181, v151
	v_alignbit_b32 v108, v183, v182, v151
	v_alignbit_b32 v109, v184, v183, v151
	v_alignbit_b32 v118, v187, v186, v151
	v_alignbit_b32 v119, v188, v187, v151
	v_alignbit_b32 v120, v189, v188, v151
	v_alignbit_b32 v121, v190, v189, v151
	ds_read2_b32 v[180:181], v176 offset1:1
	ds_read2_b32 v[182:183], v176 offset0:2 offset1:3
	ds_read_b32 v184, v176 offset:16
	ds_read2_b32 v[186:187], v176 offset0:8 offset1:9
	ds_read2_b32 v[188:189], v176 offset0:10 offset1:11
	ds_read_b32 v190, v176 offset:48
	ds_read2_b32 v[192:193], v176 offset0:16 offset1:17
	ds_read2_b32 v[194:195], v176 offset0:18 offset1:19
	ds_read_b32 v196, v176 offset:80
	ds_read2_b32 v[198:199], v176 offset0:24 offset1:25
	ds_read2_b32 v[200:201], v176 offset0:26 offset1:27
	ds_read_b32 v202, v176 offset:112
	s_branch .LBB0_1112

; __device__ __forceinline__ bf16x8 hy_afrag(const bf16_t* gbase, const bool t2, const bool t1, const unsigned sh) {
;   const uint4 lo = *(const uint4*)gbase, hi = *(const uint4*)(gbase + 8);
;   const unsigned x0 = t2 ? lo.z : lo.x, x1 = t2 ? lo.w : lo.y, x2 = t2 ? hi.x : lo.z, x3 = t2 ? hi.y : lo.w,
;                  x4 = t2 ? hi.z : hi.x, x5 = t2 ? hi.w : hi.y;
;   const unsigned y0 = t1 ? x1 : x0, y1 = t1 ? x2 : x1, y2 = t1 ? x3 : x2, y3 = t1 ? x4 : x3, y4 = t1 ? x5 : x4;
;   union { unsigned u[4]; bf16x8 v; } o;
;   o.u[0] = __builtin_amdgcn_alignbit(y1, y0, sh);
;   o.u[1] = __builtin_amdgcn_alignbit(y2, y1, sh);
;   o.u[2] = __builtin_amdgcn_alignbit(y3, y2, sh);
;   o.u[3] = __builtin_amdgcn_alignbit(y4, y3, sh);
;   return o.v;
; template <int LSEL>
; __device__ __forceinline__ void hy_conv(const bf16_t* Z, const bf16_t* G, f32x4 (&acc)[4][4], int w, int lane) {
;     ...
;   for (int d = i_lo - (NB - 1); d <= i_hi; ++d) {
;     bf16x8 bf[4][2];
; #pragma unroll
;     for (int k = 0; k < 4; ++k) {
;       int js = (q0 + k) * BPT - d;
;       js = min(max(js, LSEL ? -1 : 0), NB - 1);
;       const bf16_t* bp = Z + zb + 64 * js;
;       bf[k][0] = *(const bf16x8*)bp;
;       bf[k][1] = *(const bf16x8*)(bp + 32);
;     }
;     const bf16_t* gb = G + (L - 64 * d + 8 * quad - r - s);
;     bf16x8 F[6];
; #pragma unroll
;     for (int u = 0; u < 6; ++u) F[u] = hy_afrag(gb + 16 * (u - 3), t2, t1, sh);
; #pragma unroll
;     for (int k = 0; k < 4; ++k) {
;       const int js = (q0 + k) * BPT - d;
;       const bool valid = LSEL ? (js >= -1 && js <= NB - 1) : (js >= 0 && js <= NB - 1);
;       if (valid) {
; #pragma unroll
;         for (int mt = 0; mt < 4; ++mt) {
;           acc[k][mt] = __builtin_amdgcn_mfma_f32_16x16x32_bf16(F[3 - mt], bf[k][0], acc[k][mt], 0, 0, 0);
;           acc[k][mt] = __builtin_amdgcn_mfma_f32_16x16x32_bf16(F[5 - mt], bf[k][1], acc[k][mt], 0, 0, 0);
;         }
;       }
;     }
.LBB0_1112:
	s_waitcnt lgkmcnt(0)
	v_mov_b32_e32 v138, v106
	v_mov_b32_e32 v139, v107
	v_mov_b32_e32 v140, v108
	v_mov_b32_e32 v141, v109
	v_mov_b32_e32 v142, v118
	v_mov_b32_e32 v143, v119
	v_mov_b32_e32 v144, v120
	v_mov_b32_e32 v145, v121
	v_alignbit_b32 v106, v181, v180, v151
	v_alignbit_b32 v107, v182, v181, v151
	v_alignbit_b32 v108, v183, v182, v151
	v_alignbit_b32 v109, v184, v183, v151
	v_alignbit_b32 v118, v187, v186, v151
	v_alignbit_b32 v119, v188, v187, v151
	v_alignbit_b32 v120, v189, v188, v151
	v_alignbit_b32 v121, v190, v189, v151
	v_alignbit_b32 v122, v193, v192, v151
	v_alignbit_b32 v123, v194, v193, v151
	v_alignbit_b32 v124, v195, v194, v151
	v_alignbit_b32 v125, v196, v195, v151
	v_alignbit_b32 v134, v199, v198, v151
	v_alignbit_b32 v135, v200, v199, v151
	v_alignbit_b32 v136, v201, v200, v151
	v_alignbit_b32 v137, v202, v201, v151
	s_add_i32 s10, s9, 1
	v_med3_i32 v0, s10, -1, 63
	v_lshl_add_u32 v0, v0, 7, v154
	s_add_i32 s10, s9, 3
	ds_read_b128 v[126:129], v0 offset:128
	ds_read_b128 v[130:133], v0 offset:192
	v_med3_i32 v0, s10, -1, 63
	s_add_i32 s10, s9, 5
	v_lshl_add_u32 v0, v0, 7, v154
	s_min_i32 s10, s10, 63
	ds_read_b128 v[110:113], v0 offset:128
	ds_read_b128 v[114:117], v0 offset:192
	v_lshl_add_u32 v0, s10, 7, v154
	ds_read_b128 v[98:101], v0 offset:128
	ds_read_b128 v[102:105], v0 offset:192
	v_add_u32_e32 v0, s8, v155
	ds_read_b128 v[168:171], v0
	ds_read_b128 v[172:175], v0 offset:64
	v_add_u32_e32 v0, s8, v176
	v_add_u32_e32 v0, 0xffffff80, v0
	ds_read2_b32 v[180:181], v0 offset1:1
	ds_read2_b32 v[182:183], v0 offset0:2 offset1:3
	ds_read_b32 v184, v0 offset:16
	ds_read2_b32 v[186:187], v0 offset0:8 offset1:9
	ds_read2_b32 v[188:189], v0 offset0:10 offset1:11
	ds_read_b32 v190, v0 offset:48
	s_waitcnt lgkmcnt(6)
	ds_read2_b32 v[192:193], v0 offset0:16 offset1:17
	ds_read2_b32 v[194:195], v0 offset0:18 offset1:19
	ds_read_b32 v196, v0 offset:80
	ds_read2_b32 v[198:199], v0 offset0:24 offset1:25
	ds_read2_b32 v[200:201], v0 offset0:26 offset1:27
	ds_read_b32 v202, v0 offset:112
	s_cmp_gt_u32 s9, 64
	s_cbranch_scc1 .LBB0_1116
	v_mfma_f32_16x16x32_bf16 v[94:97], v[134:137], v[168:171], v[94:97]
	v_mfma_f32_16x16x32_bf16 v[90:93], v[122:125], v[168:171], v[90:93]
	v_mfma_f32_16x16x32_bf16 v[86:89], v[118:121], v[168:171], v[86:89]
	v_mfma_f32_16x16x32_bf16 v[82:85], v[106:109], v[168:171], v[82:85]
	v_mfma_f32_16x16x32_bf16 v[94:97], v[142:145], v[172:175], v[94:97]
	v_mfma_f32_16x16x32_bf16 v[90:93], v[138:141], v[172:175], v[90:93]
	v_mfma_f32_16x16x32_bf16 v[86:89], v[134:137], v[172:175], v[86:89]
	v_mfma_f32_16x16x32_bf16 v[82:85], v[122:125], v[172:175], v[82:85]
	s_add_i32 s10, s9, 2
	s_cmp_gt_u32 s10, 64
	s_cbranch_scc0 .LBB0_1117

; template <int LSEL>
; __device__ __forceinline__ void hy_conv(const bf16_t* Z, const bf16_t* G, f32x4 (&acc)[4][4], int w, int lane) {
;     ...
;   for (int d = i_lo - (NB - 1); d <= i_hi; ++d) {
;     bf16x8 bf[4][2];
; #pragma unroll
;     for (int k = 0; k < 4; ++k) {
;       int js = (q0 + k) * BPT - d;
;       js = min(max(js, LSEL ? -1 : 0), NB - 1);
;       const bf16_t* bp = Z + zb + 64 * js;
;       bf[k][0] = *(const bf16x8*)bp;
;       bf[k][1] = *(const bf16x8*)(bp + 32);
;     }
;     const bf16_t* gb = G + (L - 64 * d + 8 * quad - r - s);
;     bf16x8 F[6];
; #pragma unroll
;     for (int u = 0; u < 6; ++u) F[u] = hy_afrag(gb + 16 * (u - 3), t2, t1, sh);
; template <int LSEL>
; __device__ void hyena_half(const Params& p, int c, int dry) {
;     ...
;   f32x4 acc[4][4];
; #pragma unroll
;   for (int k = 0; k < 4; ++k)
; #pragma unroll
;     for (int mt = 0; mt < 4; ++mt) acc[k][mt] = f32x4{0.f, 0.f, 0.f, 0.f};
.LBB0_1203:
	s_or_b64 exec, exec, s[8:9]
	v_mov_b32_e32 v2, v1
	v_mov_b32_e32 v3, v1
	v_mov_b32_e32 v0, v1
	v_mov_b64_e32 v[8:9], v[2:3]
	v_mov_b64_e32 v[12:13], v[2:3]
	v_mov_b64_e32 v[16:17], v[2:3]
	v_mov_b64_e32 v[20:21], v[2:3]
	v_mov_b64_e32 v[24:25], v[2:3]
	v_mov_b64_e32 v[28:29], v[2:3]
	v_mov_b64_e32 v[32:33], v[2:3]
	v_mov_b64_e32 v[36:37], v[2:3]
	v_mov_b64_e32 v[40:41], v[2:3]
	v_mov_b64_e32 v[48:49], v[2:3]
	v_mov_b64_e32 v[52:53], v[2:3]
	v_mov_b64_e32 v[56:57], v[2:3]
	v_mov_b64_e32 v[60:61], v[2:3]
	v_mov_b64_e32 v[64:65], v[2:3]
	v_mov_b64_e32 v[68:69], v[2:3]
	v_mov_b64_e32 v[76:77], v[2:3]
	s_mov_b32 s8, 64
	s_mov_b32 s9, 0
	v_mov_b64_e32 v[6:7], v[0:1]
	v_mov_b64_e32 v[10:11], v[0:1]
	v_mov_b64_e32 v[14:15], v[0:1]
	v_mov_b64_e32 v[18:19], v[0:1]
	v_mov_b64_e32 v[22:23], v[0:1]
	v_mov_b64_e32 v[26:27], v[0:1]
	v_mov_b64_e32 v[30:31], v[0:1]
	v_mov_b64_e32 v[34:35], v[0:1]
	v_mov_b64_e32 v[38:39], v[0:1]
	v_mov_b64_e32 v[46:47], v[0:1]
	v_mov_b64_e32 v[50:51], v[0:1]
	v_mov_b64_e32 v[54:55], v[0:1]
	v_mov_b64_e32 v[58:59], v[0:1]
	v_mov_b64_e32 v[62:63], v[0:1]
	v_mov_b64_e32 v[66:67], v[0:1]
	v_mov_b64_e32 v[74:75], v[0:1]
	s_waitcnt lgkmcnt(0)
	s_barrier
	ds_read2_b32 v[180:181], v176 offset0:32 offset1:33
	ds_read2_b32 v[182:183], v176 offset0:34 offset1:35
	ds_read_b32 v184, v176 offset:144
	ds_read2_b32 v[186:187], v176 offset0:40 offset1:41
	ds_read2_b32 v[188:189], v176 offset0:42 offset1:43
	ds_read_b32 v190, v176 offset:176
	s_waitcnt lgkmcnt(0)
	v_alignbit_b32 v106, v181, v180, v151
	v_alignbit_b32 v107, v182, v181, v151
	v_alignbit_b32 v108, v183, v182, v151
	v_alignbit_b32 v109, v184, v183, v151
	v_alignbit_b32 v118, v187, v186, v151
	v_alignbit_b32 v119, v188, v187, v151
	v_alignbit_b32 v120, v189, v188, v151
	v_alignbit_b32 v121, v190, v189, v151
	ds_read2_b32 v[180:181], v176 offset1:1
	ds_read2_b32 v[182:183], v176 offset0:2 offset1:3
	ds_read_b32 v184, v176 offset:16
	ds_read2_b32 v[186:187], v176 offset0:8 offset1:9
	ds_read2_b32 v[188:189], v176 offset0:10 offset1:11
	ds_read_b32 v190, v176 offset:48
	ds_read2_b32 v[192:193], v176 offset0:16 offset1:17
	ds_read2_b32 v[194:195], v176 offset0:18 offset1:19
	ds_read_b32 v196, v176 offset:80
	ds_read2_b32 v[198:199], v176 offset0:24 offset1:25
	ds_read2_b32 v[200:201], v176 offset0:26 offset1:27
	ds_read_b32 v202, v176 offset:112
	s_branch .LBB0_1205

; __device__ __forceinline__ bf16x8 hy_afrag(const bf16_t* gbase, const bool t2, const bool t1, const unsigned sh) {
;   const uint4 lo = *(const uint4*)gbase, hi = *(const uint4*)(gbase + 8);
;   const unsigned x0 = t2 ? lo.z : lo.x, x1 = t2 ? lo.w : lo.y, x2 = t2 ? hi.x : lo.z, x3 = t2 ? hi.y : lo.w,
;                  x4 = t2 ? hi.z : hi.x, x5 = t2 ? hi.w : hi.y;
;   const unsigned y0 = t1 ? x1 : x0, y1 = t1 ? x2 : x1, y2 = t1 ? x3 : x2, y3 = t1 ? x4 : x3, y4 = t1 ? x5 : x4;
;   union { unsigned u[4]; bf16x8 v; } o;
;   o.u[0] = __builtin_amdgcn_alignbit(y1, y0, sh);
;   o.u[1] = __builtin_amdgcn_alignbit(y2, y1, sh);
;   o.u[2] = __builtin_amdgcn_alignbit(y3, y2, sh);
;   o.u[3] = __builtin_amdgcn_alignbit(y4, y3, sh);
;   return o.v;
; template <int LSEL>
; __device__ __forceinline__ void hy_conv(const bf16_t* Z, const bf16_t* G, f32x4 (&acc)[4][4], int w, int lane) {
;     ...
;   for (int d = i_lo - (NB - 1); d <= i_hi; ++d) {
;     bf16x8 bf[4][2];
; #pragma unroll
;     for (int k = 0; k < 4; ++k) {
;       int js = (q0 + k) * BPT - d;
;       js = min(max(js, LSEL ? -1 : 0), NB - 1);
;       const bf16_t* bp = Z + zb + 64 * js;
;       bf[k][0] = *(const bf16x8*)bp;
;       bf[k][1] = *(const bf16x8*)(bp + 32);
;     }
;     const bf16_t* gb = G + (L - 64 * d + 8 * quad - r - s);
;     bf16x8 F[6];
; #pragma unroll
;     for (int u = 0; u < 6; ++u) F[u] = hy_afrag(gb + 16 * (u - 3), t2, t1, sh);
; #pragma unroll
;     for (int k = 0; k < 4; ++k) {
;       const int js = (q0 + k) * BPT - d;
;       const bool valid = LSEL ? (js >= -1 && js <= NB - 1) : (js >= 0 && js <= NB - 1);
;       if (valid) {
; #pragma unroll
;         for (int mt = 0; mt < 4; ++mt) {
;           acc[k][mt] = __builtin_amdgcn_mfma_f32_16x16x32_bf16(F[3 - mt], bf[k][0], acc[k][mt], 0, 0, 0);
;           acc[k][mt] = __builtin_amdgcn_mfma_f32_16x16x32_bf16(F[5 - mt], bf[k][1], acc[k][mt], 0, 0, 0);
;         }
;       }
;     }
.LBB0_1205:
	s_waitcnt lgkmcnt(0)
	v_mov_b32_e32 v138, v106
	v_mov_b32_e32 v139, v107
	v_mov_b32_e32 v140, v108
	v_mov_b32_e32 v141, v109
	v_mov_b32_e32 v142, v118
	v_mov_b32_e32 v143, v119
	v_mov_b32_e32 v144, v120
	v_mov_b32_e32 v145, v121
	v_alignbit_b32 v106, v181, v180, v151
	v_alignbit_b32 v107, v182, v181, v151
	v_alignbit_b32 v108, v183, v182, v151
	v_alignbit_b32 v109, v184, v183, v151
	v_alignbit_b32 v118, v187, v186, v151
	v_alignbit_b32 v119, v188, v187, v151
	v_alignbit_b32 v120, v189, v188, v151
	v_alignbit_b32 v121, v190, v189, v151
	v_alignbit_b32 v122, v193, v192, v151
	v_alignbit_b32 v123, v194, v193, v151
	v_alignbit_b32 v124, v195, v194, v151
	v_alignbit_b32 v125, v196, v195, v151
	v_alignbit_b32 v134, v199, v198, v151
	v_alignbit_b32 v135, v200, v199, v151
	v_alignbit_b32 v136, v201, v200, v151
	v_alignbit_b32 v137, v202, v201, v151
	s_add_i32 s10, s8, 1
	v_med3_i32 v0, s10, -1, 63
	v_lshl_add_u32 v0, v0, 7, v154
	s_add_i32 s10, s8, 3
	ds_read_b128 v[126:129], v0 offset:128
	ds_read_b128 v[130:133], v0 offset:192
	v_med3_i32 v0, s10, -1, 63
	s_add_i32 s10, s8, 5
	v_lshl_add_u32 v0, v0, 7, v154
	s_min_i32 s10, s10, 63
	ds_read_b128 v[110:113], v0 offset:128
	ds_read_b128 v[114:117], v0 offset:192
	v_lshl_add_u32 v0, s10, 7, v154
	ds_read_b128 v[98:101], v0 offset:128
	ds_read_b128 v[102:105], v0 offset:192
	v_add_u32_e32 v0, s9, v155
	ds_read_b128 v[168:171], v0
	ds_read_b128 v[172:175], v0 offset:64
	v_add_u32_e32 v0, s9, v176
	v_add_u32_e32 v0, 0xffffff80, v0
	ds_read2_b32 v[180:181], v0 offset1:1
	ds_read2_b32 v[182:183], v0 offset0:2 offset1:3
	ds_read_b32 v184, v0 offset:16
	ds_read2_b32 v[186:187], v0 offset0:8 offset1:9
	ds_read2_b32 v[188:189], v0 offset0:10 offset1:11
	ds_read_b32 v190, v0 offset:48
	s_waitcnt lgkmcnt(6)
	ds_read2_b32 v[192:193], v0 offset0:16 offset1:17
	ds_read2_b32 v[194:195], v0 offset0:18 offset1:19
	ds_read_b32 v196, v0 offset:80
	ds_read2_b32 v[198:199], v0 offset0:24 offset1:25
	ds_read2_b32 v[200:201], v0 offset0:26 offset1:27
	ds_read_b32 v202, v0 offset:112
	s_cmp_gt_u32 s8, 64
	s_cbranch_scc1 .LBB0_1209
	v_mfma_f32_16x16x32_bf16 v[74:77], v[134:137], v[168:171], v[74:77]
	v_mfma_f32_16x16x32_bf16 v[66:69], v[122:125], v[168:171], v[66:69]
	v_mfma_f32_16x16x32_bf16 v[62:65], v[118:121], v[168:171], v[62:65]
	v_mfma_f32_16x16x32_bf16 v[58:61], v[106:109], v[168:171], v[58:61]
	v_mfma_f32_16x16x32_bf16 v[74:77], v[142:145], v[172:175], v[74:77]
	v_mfma_f32_16x16x32_bf16 v[66:69], v[138:141], v[172:175], v[66:69]
	v_mfma_f32_16x16x32_bf16 v[62:65], v[134:137], v[172:175], v[62:65]
	v_mfma_f32_16x16x32_bf16 v[58:61], v[122:125], v[172:175], v[58:61]
	s_add_i32 s10, s8, 2
	s_cmp_gt_u32 s10, 64
	s_cbranch_scc0 .LBB0_1210
